# main GEMM: no per-phase flips, static s_setprio 1 for waves 0-3
# baseline (speedup 1.0000x reference)
; #define WAIT_V(n) asm volatile("s_waitcnt vmcnt(" #n ")" ::: "memory")
; #define BAR __builtin_amdgcn_s_barrier()
; #define STG(P, PTR, LD, O0) do { const bf16_t* _g = (PTR); \
;     __builtin_amdgcn_global_load_lds((const unsigned*)(_g + O0), (lds_u32*)((P) + swave * 1024), 16, 0, 0); \
;     __builtin_amdgcn_global_load_lds((const unsigned*)(_g + (size_t)64 * (LD) + O0), (lds_u32*)((P) + swave * 1024 + 8192), 16, 0, 0); } while (0)
; #define WAIT_V(n) asm volatile("s_waitcnt vmcnt(" #n ")" ::: "memory")
; #define BAR __builtin_amdgcn_s_barrier()
; __device__ __forceinline__ void gemm_stream(int swave, const GemmJob& J, char* shm, int vb, int G) {
;     ...
;   const int wid = tidx >> 6, lane = tidx & 63, wr = wid >> 2, wc = wid & 3, fr = lane & 15, fq = lane >> 4;
;   unsigned offA0, offA1, offB0;
;   { int _r, _c; stage_rc(tidx * 16, _r, _c); offA0 = _r * lda + _c; offA1 = _r * lda1 + _c; const int _rb = (_r & ~31) + perm32(_r & 31); offB0 = _rb * ldb + _c; }
;   const size_t hB = (size_t)128 * ldb;
;   int cg, cbrow, cbcol; const bf16_t* cA; const bf16_t* cA1; const bf16_t* cB;
;   auto decode = [&](int id, int& g, int& brow, int& bcol, const bf16_t*& pA, const bf16_t*& pA1, const bf16_t*& pB) {
;     int pm, pn; g = 0;
;     if (J.nb == 1) tile_map(id, J.nM, J.nN, pm, pn);
;     else { g = id / per; const int rem = id - g * per; pm = rem / J.nN; pn = rem - pm * J.nN; }
;     brow = pm * 256; bcol = pn * 256;
;     pA = J.A + (size_t)g * J.strideA + (size_t)brow * lda; pA1 = J.A1 + (size_t)g * J.strideA + (size_t)brow * lda1; pB = J.Bt + (size_t)g * J.strideB + (size_t)bcol * ldb;
;   };
;   int id = vb;
;   decode(id, cg, cbrow, cbcol, cA, cA1, cB);
;   f32x4 acc[2][2][4][2] = {};
;   bf16x8 At[4][2], B0[2][2], B1[2][2];
;   STG(SB(0, 0), cB, ldb, offB0); STGA(SA(0, 0), cA, cA1, 0, 0); STG(SB(0, 1), cB + hB, ldb, offB0); STGA(SA(0, 1), cA, cA1, 0, 1);
;   if (wr == 1) BAR;
;   WAIT_V(4); BAR;
;   STG(SB(1, 0), cB + 64, ldb, offB0); STGA(SA(1, 0), cA, cA1, 1, 0); STG(SB(1, 1), cB + hB + 64, ldb, offB0);
;   WAIT_V(6); BAR;
.LBB0_725:
	s_or_b64 exec, exec, s[6:7]
	v_mad_u64_u32 v[138:139], s[6:7], v17, s37, v[2:3]
	s_mul_i32 s6, s10, s37
	s_mul_hi_u32 s7, s5, s37
	s_add_i32 s7, s7, s6
	s_mul_i32 s6, s5, s37
	s_lshr_b32 s49, s76, 6
	s_lshl_b64 s[6:7], s[6:7], 1
	v_readlane_b32 s10, v247, 55
	v_readlane_b32 s11, v247, 56
	s_add_u32 s16, s10, s6
	s_addc_u32 s17, s11, s7
	s_add_u32 s50, s10, 0xc000000
	v_readlane_b32 s7, v247, 28
	s_addc_u32 s51, s11, 0
	s_add_i32 s6, s7, s89
	v_lshl_add_u64 v[4:5], v[4:5], 0, s[22:23]
	s_mov_b32 m0, s6
	s_waitcnt vmcnt(4)
	s_barrier
	global_load_lds_dwordx4 v[4:5], off
	v_lshl_add_u64 v[4:5], v[6:7], 0, s[22:23]
	s_add_i32 m0, s6, 0x2000
	s_add_i32 s54, s42, 0x8000
	global_load_lds_dwordx4 v[4:5], off
	v_lshl_add_u64 v[4:5], v[8:9], 0, s[22:23]
	s_mov_b32 m0, s54
	s_add_i32 s55, s42, 0xa000
	v_readlane_b32 s10, v247, 29
	global_load_lds_dwordx4 v[4:5], off
	v_lshl_add_u64 v[4:5], v[10:11], 0, s[22:23]
	s_mov_b32 m0, s55
	s_add_i32 s6, s10, s89
	global_load_lds_dwordx4 v[4:5], off
	v_lshl_add_u64 v[4:5], v[12:13], 0, s[22:23]
	s_mov_b32 m0, s6
	v_and_b32_e32 v1, 15, v135
	global_load_lds_dwordx4 v[4:5], off
	v_lshl_add_u64 v[4:5], v[14:15], 0, s[22:23]
	s_add_i32 m0, s6, 0x2000
	v_bfe_u32 v19, v135, 4, 2
	global_load_lds_dwordx4 v[4:5], off
	v_lshlrev_b32_e32 v4, 2, v135
	v_lshlrev_b32_e32 v6, 4, v19
	v_lshlrev_b32_e32 v2, 6, v1
	v_and_b32_e32 v7, 32, v4
	v_bitop3_b32 v8, v6, v7, v2 bitop3:0x36
	s_add_i32 s6, 0, 0x10000
	v_add_u32_e32 v9, s6, v8
	s_add_i32 s6, 0, 0x14000
	v_add_u32_e32 v10, s6, v8
	v_lshlrev_b32_e32 v14, 6, v135
	s_movk_i32 s6, 0x3c0
	v_bfe_u32 v18, v135, 6, 2
	s_waitcnt vmcnt(6)
	v_lshlrev_b32_e32 v13, 13, v16
	v_and_or_b32 v6, v14, s6, v6
	v_lshlrev_b32_e32 v5, 12, v18
	v_add_u32_e32 v11, s7, v8
	v_add_u32_e32 v12, s10, v8
	v_lshlrev_b32_e32 v2, 5, v18
	v_lshlrev_b32_e32 v4, 3, v19
	v_add_u32_e32 v8, 0, v8
	v_xad_u32 v6, v6, v7, 0
	v_or_b32_e32 v7, 0x800, v13
	v_or_b32_e32 v14, 0x1000, v13
	v_or_b32_e32 v15, 0x1800, v13
	v_lshl_or_b32 v1, v16, 6, v1
	v_add_u32_e32 v139, v9, v5
	v_add_u32_e32 v144, v8, v13
	v_add_u32_e32 v145, v6, v7
	v_add_u32_e32 v159, v6, v14
	v_add_u32_e32 v160, v6, v15
	v_add_u32_e32 v161, v10, v5
	v_add_u32_e32 v162, v11, v5
	v_add_u32_e32 v163, v12, v5
	v_lshlrev_b32_e32 v140, 1, v2
	v_lshlrev_b32_e32 v142, 1, v4
	s_mov_b64 s[10:11], s[8:9]
	s_mov_b64 s[12:13], s[16:17]
	s_mov_b64 s[14:15], s[2:3]
	s_barrier
	v_readfirstlane_b32 s6, v135
	s_cmpk_lt_u32 s6, 0x100
	s_cbranch_scc0 .Lgemm_prio_skip
	s_setprio 1
